# remaining grid barriers (P1->P2, P2->P3, P6->P7) use a one-level arrival sharded by blockIdx&7; waiters read all 8 counters in one round
# speedup vs baseline: 1.0059x; 1.0059x over previous
; __device__ __forceinline__ unsigned xb_ld(unsigned* p) { return __hip_atomic_load(p, __ATOMIC_RELAXED, __HIP_MEMORY_SCOPE_AGENT); }
; __device__ __forceinline__ unsigned xb_add(unsigned* p, unsigned v) { return __hip_atomic_fetch_add(p, v, __ATOMIC_RELAXED, __HIP_MEMORY_SCOPE_AGENT); }
; __device__ __forceinline__ void xcd_barrier(const XB& b) {
;     __syncthreads();
;     if (threadIdx.x == 0) {
;         unsigned* bar = b.bar;
;         __builtin_amdgcn_fence(__ATOMIC_RELEASE, "agent");
;         asm volatile("s_waitcnt vmcnt(0)" ::: "memory");
;         const unsigned old = xb_add(&bar[XB_XSUB(b.x)], 1u);
;         const unsigned gen = old / b.nloc;
;         if (old + 1u == (gen + 1u) * b.nloc) {
;             const unsigned og = xb_add(&bar[XB_TOP], 1u);
;             const unsigned target = (og / b.nx + 1u) * b.nx;
;             if (og + 1u != target) while (xb_ld(&bar[XB_TOP]) < target) __builtin_amdgcn_s_sleep(1);
;             xb_add(&bar[XB_XGEN(b.x)], 1u);
;         } else {
;             while (xb_ld(&bar[XB_XGEN(b.x)]) == gen) __builtin_amdgcn_s_sleep(1);
;         }
;         __builtin_amdgcn_fence(__ATOMIC_ACQUIRE, "agent");
;         asm volatile("s_waitcnt vmcnt(0)" ::: "memory");
;     }
;     __syncthreads();
; }
.Linvw_5:
	s_mov_b64 s[0:1], exec
	v_readlane_b32 s6, v253, 2
	v_readlane_b32 s7, v253, 3
	s_and_b64 s[6:7], s[0:1], s[6:7]
	s_mov_b64 exec, s[6:7]
	s_cbranch_execz .LBB0_113
	s_cmpk_lg_i32 s33, 0x100
	s_cbranch_scc1 .Lfb_b1_orig
	s_and_b32 s97, s2, 7
	s_lshl_b32 s97, s97, 6
	s_add_i32 s97, s97, 0x1b6e90c
	v_mov_b32_e32 v24, s97
	v_mov_b32_e32 v25, 1
	global_atomic_add v24, v25, s[82:83]
	v_mov_b32_e32 v34, 0x1b6e90c
.Lfb_b1_poll:
	global_load_dword v26, v34, s[82:83] offset:0 sc1
	global_load_dword v27, v34, s[82:83] offset:64 sc1
	global_load_dword v28, v34, s[82:83] offset:128 sc1
	global_load_dword v29, v34, s[82:83] offset:192 sc1
	global_load_dword v30, v34, s[82:83] offset:256 sc1
	global_load_dword v31, v34, s[82:83] offset:320 sc1
	global_load_dword v32, v34, s[82:83] offset:384 sc1
	global_load_dword v33, v34, s[82:83] offset:448 sc1
	s_waitcnt vmcnt(0)
	v_min_u32_e32 v26, v26, v27
	v_min_u32_e32 v28, v28, v29
	v_min_u32_e32 v30, v30, v31
	v_min_u32_e32 v32, v32, v33
	v_min_u32_e32 v26, v26, v28
	v_min_u32_e32 v30, v30, v32
	v_min_u32_e32 v26, v26, v30
	v_readfirstlane_b32 s97, v26
	s_cmp_lt_u32 s97, 32
	s_cbranch_scc0 .LBB0_113
	s_sleep 1
	s_branch .Lfb_b1_poll
.Lfb_b1_orig:
	s_mov_b64 s[8:9], exec
	s_nop 0
	s_waitcnt vmcnt(0)
	s_lshl_b32 s3, s89, 8
	v_readlane_b32 s6, v253, 0
	v_mbcnt_lo_u32_b32 v0, s8, 0
	v_readlane_b32 s7, v253, 1
	s_add_u32 s6, s6, s3
	v_mbcnt_hi_u32_b32 v0, s9, v0
	s_addc_u32 s7, s7, 0
	v_cmp_eq_u32_e32 vcc, 0, v0
	s_and_saveexec_b64 s[10:11], vcc
	s_cbranch_execz .LBB0_97
	s_bcnt1_i32_b64 s3, s[8:9]
	v_mov_b32_e32 v1, 0x1000
	v_mov_b32_e32 v2, s3
	global_atomic_add v1, v1, v2, s[6:7] sc0

; __device__ __forceinline__ unsigned xb_ld(unsigned* p) { return __hip_atomic_load(p, __ATOMIC_RELAXED, __HIP_MEMORY_SCOPE_AGENT); }
; __device__ __forceinline__ unsigned xb_add(unsigned* p, unsigned v) { return __hip_atomic_fetch_add(p, v, __ATOMIC_RELAXED, __HIP_MEMORY_SCOPE_AGENT); }
; __device__ __forceinline__ void xcd_barrier(const XB& b) {
;     __syncthreads();
;     if (threadIdx.x == 0) {
;         unsigned* bar = b.bar;
;         __builtin_amdgcn_fence(__ATOMIC_RELEASE, "agent");
;         asm volatile("s_waitcnt vmcnt(0)" ::: "memory");
;         const unsigned old = xb_add(&bar[XB_XSUB(b.x)], 1u);
;         const unsigned gen = old / b.nloc;
;         if (old + 1u == (gen + 1u) * b.nloc) {
;             const unsigned og = xb_add(&bar[XB_TOP], 1u);
;             const unsigned target = (og / b.nx + 1u) * b.nx;
;             if (og + 1u != target) while (xb_ld(&bar[XB_TOP]) < target) __builtin_amdgcn_s_sleep(1);
;             xb_add(&bar[XB_XGEN(b.x)], 1u);
;         } else {
;             while (xb_ld(&bar[XB_XGEN(b.x)]) == gen) __builtin_amdgcn_s_sleep(1);
;         }
;         __builtin_amdgcn_fence(__ATOMIC_ACQUIRE, "agent");
;         asm volatile("s_waitcnt vmcnt(0)" ::: "memory");
;     }
;     __syncthreads();
; }
.Linvw_4:
	s_mov_b64 s[0:1], exec
	v_readlane_b32 s4, v253, 2
	v_readlane_b32 s5, v253, 3
	s_and_b64 s[4:5], s[0:1], s[4:5]
	s_mov_b64 exec, s[4:5]
	s_cbranch_execz .LBB0_308
	s_cmpk_lg_i32 s33, 0x100
	s_cbranch_scc1 .Lfb_b2_orig
	buffer_wbl2 sc1
	s_waitcnt vmcnt(0)
	s_and_b32 s97, s2, 7
	s_lshl_b32 s97, s97, 6
	s_add_i32 s97, s97, 0x1b6eb0c
	v_mov_b32_e32 v24, s97
	v_mov_b32_e32 v25, 1
	global_atomic_add v24, v25, s[82:83]
	v_mov_b32_e32 v34, 0x1b6eb0c

; __device__ __forceinline__ unsigned xb_ld(unsigned* p) { return __hip_atomic_load(p, __ATOMIC_RELAXED, __HIP_MEMORY_SCOPE_AGENT); }
; __device__ __forceinline__ unsigned xb_add(unsigned* p, unsigned v) { return __hip_atomic_fetch_add(p, v, __ATOMIC_RELAXED, __HIP_MEMORY_SCOPE_AGENT); }
; __device__ __forceinline__ void xcd_barrier(const XB& b) {
;     __syncthreads();
;     if (threadIdx.x == 0) {
;         unsigned* bar = b.bar;
;         __builtin_amdgcn_fence(__ATOMIC_RELEASE, "agent");
;         asm volatile("s_waitcnt vmcnt(0)" ::: "memory");
;         const unsigned old = xb_add(&bar[XB_XSUB(b.x)], 1u);
;         const unsigned gen = old / b.nloc;
;         if (old + 1u == (gen + 1u) * b.nloc) {
;             const unsigned og = xb_add(&bar[XB_TOP], 1u);
;             const unsigned target = (og / b.nx + 1u) * b.nx;
;             if (og + 1u != target) while (xb_ld(&bar[XB_TOP]) < target) __builtin_amdgcn_s_sleep(1);
;             xb_add(&bar[XB_XGEN(b.x)], 1u);
;         } else {
;             while (xb_ld(&bar[XB_XGEN(b.x)]) == gen) __builtin_amdgcn_s_sleep(1);
;         }
;         __builtin_amdgcn_fence(__ATOMIC_ACQUIRE, "agent");
;         asm volatile("s_waitcnt vmcnt(0)" ::: "memory");
;     }
;     __syncthreads();
; }
; __device__ __forceinline__ void p7_final(const Params& p, bool prompt_done) {
;     ...
;     for (int s = blockIdx.x * 8 + wave; s < MS; s += stride) {
.Linvw_0:
	s_mov_b64 s[0:1], exec
	v_readlane_b32 s2, v253, 2
	v_readlane_b32 s3, v253, 3
	s_and_b64 s[2:3], s[0:1], s[2:3]
	s_mov_b64 exec, s[2:3]
	s_cbranch_execz .LBB0_637
	s_cmpk_lg_i32 s33, 0x100
	s_cbranch_scc1 .Lfb_b6_orig
	v_readfirstlane_b32 s97, v130
	s_bfe_u32 s97, s97, 0x30003
	s_lshl_b32 s97, s97, 6
	s_add_i32 s97, s97, 0x1b6ed0c
	v_mov_b32_e32 v24, s97
	v_mov_b32_e32 v25, 1
	global_atomic_add v24, v25, s[82:83]
	v_mov_b32_e32 v34, 0x1b6ed0c
	v_readfirstlane_b32 s97, v130
	s_cmpk_lt_u32 s97, 0x80
	s_cbranch_scc0 .LBB0_637
